# layer-1 w_out transposes (256 tiny items) moved from mix(l=0) to the end of mix(l=1) as fine-grained filler; needed only by GEMM2(l=1)
# speedup vs baseline: 1.0029x; 1.0017x over previous
.LBB0_633:
	s_or_b64 exec, exec, s[36:37]
	s_lshl_b32 s70, s14, 6
	s_lshl_b64 s[20:21], s[70:71], 2
	s_add_u32 s15, s30, s20
	s_addc_u32 s16, s31, s21
	s_add_u32 s20, s15, 0xf79f700
	s_waitcnt lgkmcnt(0)
	v_cvt_f32_u32_e32 v0, s14
	s_addc_u32 s21, s16, 0
	s_and_b32 s100, s2, 7
	s_nop 0
	s_lshl_b32 s101, s100, 5
	s_add_u32 s20, s20, s101
	s_addc_u32 s21, s21, 0
	v_writelane_b32 v254, s100, 0
	s_lshr_b32 s101, s2, 3
	s_add_i32 s101, s101, 1
	v_writelane_b32 v254, s101, 1
	v_writelane_b32 v251, s20, 37
	v_writelane_b32 v253, s84, 10
	s_movk_i32 s15, 0xac
	v_writelane_b32 v251, s21, 38
	s_and_b64 s[20:21], s[84:85], exec
	s_cselect_b32 s15, s15, 0x88
	s_cselect_b32 s100, 52, 16
	s_movk_i32 s101, 0x4e8
	s_cselect_b32 s101, 0x348, s101
	v_writelane_b32 v254, s100, 2
	v_writelane_b32 v254, s101, 3
	s_lshl_b32 s16, s14, 16
	v_mul_f32_e32 v0, 0xbe99999a, v0
	v_writelane_b32 v251, s16, 39
	v_mul_f32_e32 v1, 0x3fb8aa3b, v0
	s_mov_b32 s16, 0x3fb8aa3b
	v_fma_f32 v2, v0, s16, -v1
	v_rndne_f32_e32 v3, v1
	v_fmac_f32_e32 v2, 0x32a5705f, v0
	v_sub_f32_e32 v1, v1, v3
	v_add_f32_e32 v1, v1, v2
	v_exp_f32_e32 v1, v1
	v_cvt_i32_f32_e32 v2, v3
	s_lshl_b32 s16, s14, 2
	v_writelane_b32 v251, s16, 40
	s_mov_b32 s16, 0xc2ce8ed0
	v_ldexp_f32 v1, v1, v2
	v_cmp_ngt_f32_e32 vcc, s16, v0
	s_mov_b32 s16, 0x42b17218
	s_lshl_b32 s38, s14, 9
	v_cndmask_b32_e32 v1, 0, v1, vcc
	v_cmp_nlt_f32_e32 vcc, s16, v0
	s_lshl_b32 s16, s14, 7
	v_writelane_b32 v251, s16, 41
	s_lshl_b32 s19, s14, 18
	v_writelane_b32 v251, s19, 42
	s_mov_b32 s40, s38
	v_writelane_b32 v253, s85, 11
	v_writelane_b32 v251, s40, 43
	s_mov_b32 s39, s71
	s_lshl_b32 s74, s14, 10
	v_writelane_b32 v251, s41, 44
	v_readlane_b32 s40, v253, 12
	s_lshl_b32 s70, s14, 8
	s_or_b32 s16, s74, 0x200
	s_lshl_b32 s36, s14, 6
	s_lshl_b64 s[38:39], s[38:39], 2
	v_readlane_b32 s48, v253, 20
	v_readlane_b32 s49, v253, 21
	s_add_u32 s19, s48, s38
	v_readlane_b32 s50, v253, 22
	v_writelane_b32 v251, s19, 45
	s_addc_u32 s19, s49, s39
	s_lshl_b64 s[38:39], s[70:71], 2
	s_mul_i32 s20, s14, 0x1200
	s_mov_b32 s21, s71
	v_readlane_b32 s51, v253, 23
	s_add_u32 s38, s50, s38
	v_readlane_b32 s54, v253, 26
	s_addc_u32 s39, s51, s39
	s_lshl_b64 s[20:21], s[20:21], 2
	s_mul_i32 s22, s14, 0x600
	s_mov_b32 s23, s71
	v_readlane_b32 s55, v253, 27
	s_add_u32 s80, s54, s20
	s_addc_u32 s81, s55, s21
	s_lshl_b64 s[20:21], s[22:23], 2
	s_mov_b32 s37, s71
	v_writelane_b32 v251, s19, 46
	s_add_u32 s82, s12, s20
	v_writelane_b32 v251, s38, 47
	s_addc_u32 s83, s13, s21
	s_lshl_b64 s[20:21], s[36:37], 2
	v_readlane_b32 s19, v252, 53
	v_writelane_b32 v251, s39, 48
	s_add_u32 s19, s19, s20
	v_writelane_b32 v251, s19, 49
	v_readlane_b32 s19, v252, 54
	s_addc_u32 s19, s19, s21
	s_add_u32 s17, s17, 0x1800000
	v_writelane_b32 v251, s19, 50
	v_writelane_b32 v251, s17, 51
	s_addc_u32 s17, s18, 0
	v_writelane_b32 v251, s17, 52
	v_readfirstlane_b32 s17, v188
	s_lshr_b32 s18, s17, 8
	s_mul_i32 s17, s18, 0x12000
	s_add_i32 s17, s17, 0
	v_writelane_b32 v251, s18, 53
	s_addk_i32 s18, 0xff80
	v_writelane_b32 v251, s18, 54
	s_add_i32 s18, s17, 0x8800
	v_writelane_b32 v251, s18, 55
	s_add_i32 s18, s17, 0x4400
	v_writelane_b32 v251, s18, 56
	s_add_i32 s18, s17, 0x800
	v_writelane_b32 v251, s18, 57
	s_mul_i32 s19, s14, 0x1a00000
	v_readlane_b32 s20, v251, 32
	s_add_u32 s19, s20, s19
	v_cndmask_b32_e32 v0, v200, v1, vcc
	v_writelane_b32 v251, s19, 58
	v_fmamk_f32 v150, v0, 0xbf19999a, v192
	s_mul_hi_u32 s18, s14, 0x1a00000
	v_readlane_b32 s19, v251, 33
	v_sub_f32_e32 v203, 1.0, v150
	s_mov_b32 s75, s71
	s_addc_u32 s18, s19, s18
	s_barrier
	v_readlane_b32 s41, v253, 13
	v_readlane_b32 s42, v253, 14
	v_readlane_b32 s43, v253, 15
	v_readlane_b32 s44, v253, 16
	v_readlane_b32 s45, v253, 17
	v_readlane_b32 s46, v253, 18
	v_readlane_b32 s47, v253, 19
	v_readlane_b32 s52, v253, 24
	v_readlane_b32 s53, v253, 25
	v_writelane_b32 v251, s18, 59
	s_branch .LBB0_637

.LBB0_641:
	s_or_b64 exec, exec, s[36:37]
	v_mov_b32_e32 v0, s1
	s_waitcnt lgkmcnt(0)
	s_barrier
	ds_read_b32 v0, v0
	s_mov_b64 s[36:37], -1
	s_waitcnt lgkmcnt(0)
	v_cmp_le_i32_e32 vcc, s15, v0
	v_readfirstlane_b32 s18, v0
	s_cbranch_vccnz .LBB0_636
	v_readlane_b32 s100, v254, 0
	s_nop 3
	v_readlane_b32 s19, v254, 2
	v_readlane_b32 s42, v254, 3
	s_nop 3
	s_mul_i32 s101, s100, s19
	s_add_i32 s101, s101, s42
	s_lshl_b32 s19, s100, 4
	s_add_i32 s42, s19, 0x2d8
	s_cmpk_lt_u32 s18, 0x78
	s_cselect_b32 s101, s42, s101
	s_add_i32 s42, s19, 0x268
	s_cmpk_lt_u32 s18, 0x68
	s_cselect_b32 s101, s42, s101
	s_add_i32 s42, s19, 0x1f8
	s_cmpk_lt_u32 s18, 0x58
	s_cselect_b32 s101, s42, s101
	s_lshl_b32 s42, s100, 5
	s_addk_i32 s42, 0x118
	s_cmpk_lt_u32 s18, 0x48
	s_cselect_b32 s101, s42, s101
	s_add_i32 s42, s19, 0xa8
	s_cmpk_lt_u32 s18, 0x28
	s_cselect_b32 s101, s42, s101
	s_add_i32 s42, s19, 56
	s_cmpk_lt_u32 s18, 0x18
	s_cselect_b32 s101, s42, s101
	s_lshl_b32 s42, s100, 3
	s_cmpk_lt_u32 s18, 8
	s_cselect_b32 s101, s42, s101
	s_add_i32 s18, s18, s101
	s_cmp_gt_i32 s18, 63
	s_cbranch_scc0 .LBB0_840
	s_lshl_b32 s42, s18, 1
	v_readlane_b32 s19, v251, 54
	s_add_i32 s19, s19, s42
	s_cmpk_gt_i32 s19, 0xff
	s_cbranch_scc0 .LBB0_775
	s_cmpk_gt_u32 s19, 0x1ff
	s_cbranch_scc0 .LBB0_751
	s_cmpk_gt_u32 s19, 0x3ff
	s_cbranch_scc0 .LBB0_704
	s_cmpk_gt_u32 s19, 0x4ff
	s_cbranch_scc0 .LBB0_696
	s_cmpk_gt_u32 s19, 0x5ff
	s_cbranch_scc0 .LBB0_673
	s_cmpk_gt_u32 s19, 0x6ff
	s_cbranch_scc0 .LBB0_654
	s_cmpk_gt_u32 s19, 0xa3f
	s_cbranch_scc0 .LBB0_651
	s_lshl_b32 s20, s19, 3
	s_and_b32 s20, s20, 0x7fffffc0
	s_add_i32 s70, s20, 0xffffae00
	s_lshl_b32 s20, s19, 8
	v_mov_b32_e32 v2, v189
	s_and_b32 s20, s20, 0x700
	s_lshl_b32 s21, s20, 2
	v_ashrrev_i32_e32 v3, 6, v2
	v_readlane_b32 s22, v252, 45
	v_add_u32_e32 v0, s70, v3
	s_add_u32 s22, s22, s21
	v_readlane_b32 s21, v252, 46
	v_lshlrev_b32_e32 v1, 4, v2
	s_addc_u32 s23, s21, 0
	v_and_b32_e32 v160, 0x3f0, v1
	v_ashrrev_i32_e32 v1, 31, v0
	v_lshl_add_u64 v[4:5], s[22:23], 0, v[160:161]
	v_lshlrev_b64 v[0:1], 13, v[0:1]
	v_lshl_add_u64 v[0:1], v[4:5], 0, v[0:1]
	global_load_dwordx4 v[24:27], v[0:1], off
	s_mov_b64 s[100:101], 0x8000
	v_lshl_add_u64 v[4:5], v[0:1], 0, s[100:101]
	global_load_dwordx4 v[28:31], v[4:5], off
	v_lshl_add_u64 v[4:5], v[4:5], 0, s[100:101]
	global_load_dwordx4 v[32:35], v[4:5], off
	v_lshl_add_u64 v[4:5], v[4:5], 0, s[100:101]
	global_load_dwordx4 v[36:39], v[4:5], off
	v_lshl_add_u64 v[4:5], v[4:5], 0, s[100:101]
	global_load_dwordx4 v[40:43], v[4:5], off
	v_lshl_add_u64 v[4:5], v[4:5], 0, s[100:101]
	global_load_dwordx4 v[44:47], v[4:5], off
	v_lshl_add_u64 v[4:5], v[4:5], 0, s[100:101]
	global_load_dwordx4 v[48:51], v[4:5], off
	v_lshl_add_u64 v[4:5], v[4:5], 0, s[100:101]
	global_load_dwordx4 v[52:55], v[4:5], off
	v_lshl_add_u64 v[4:5], v[4:5], 0, s[100:101]
	global_load_dwordx4 v[56:59], v[4:5], off
	v_lshl_add_u64 v[4:5], v[4:5], 0, s[100:101]
	global_load_dwordx4 v[60:63], v[4:5], off
	v_lshl_add_u64 v[4:5], v[4:5], 0, s[100:101]
	global_load_dwordx4 v[64:67], v[4:5], off
	v_lshl_add_u64 v[4:5], v[4:5], 0, s[100:101]
	global_load_dwordx4 v[68:71], v[4:5], off
	v_lshl_add_u64 v[4:5], v[4:5], 0, s[100:101]
	global_load_dwordx4 v[72:75], v[4:5], off
	v_lshl_add_u64 v[4:5], v[4:5], 0, s[100:101]
	global_load_dwordx4 v[76:79], v[4:5], off
	v_lshl_add_u64 v[4:5], v[4:5], 0, s[100:101]
	global_load_dwordx4 v[80:83], v[4:5], off
	v_lshl_add_u64 v[4:5], v[4:5], 0, s[100:101]
	global_load_dwordx4 v[84:87], v[4:5], off
	s_movk_i32 s36, 0x404
	v_mul_lo_u32 v3, v3, s36
	v_add3_u32 v3, s17, v160, v3
	s_lshl_b64 s[22:23], s[70:71], 1
	v_readlane_b32 s21, v252, 47
	s_nop 0
	s_add_u32 s22, s21, s22
	v_readlane_b32 s21, v252, 48
	s_nop 0
	s_addc_u32 s23, s21, s23
	s_waitcnt vmcnt(15)
	ds_write2_b32 v3, v24, v25 offset1:1
	ds_write2_b32 v3, v26, v27 offset0:2 offset1:3
	s_waitcnt vmcnt(14)
	v_add_u32_e32 v8, 0x1010, v3
	ds_write2_b32 v8, v28, v29 offset1:1
	ds_write2_b32 v8, v30, v31 offset0:2 offset1:3
	s_waitcnt vmcnt(13)
	v_add_u32_e32 v8, 0x2020, v3
	ds_write2_b32 v8, v32, v33 offset1:1
	ds_write2_b32 v8, v34, v35 offset0:2 offset1:3
	s_waitcnt vmcnt(12)
	v_add_u32_e32 v8, 0x3030, v3
	ds_write2_b32 v8, v36, v37 offset1:1
	ds_write2_b32 v8, v38, v39 offset0:2 offset1:3
	s_waitcnt vmcnt(11)
	v_add_u32_e32 v8, 0x4040, v3
	ds_write2_b32 v8, v40, v41 offset1:1
	ds_write2_b32 v8, v42, v43 offset0:2 offset1:3
	s_waitcnt vmcnt(10)
	v_add_u32_e32 v8, 0x5050, v3
	ds_write2_b32 v8, v44, v45 offset1:1
	ds_write2_b32 v8, v46, v47 offset0:2 offset1:3
	s_waitcnt vmcnt(9)
	v_add_u32_e32 v8, 0x6060, v3
	ds_write2_b32 v8, v48, v49 offset1:1
	ds_write2_b32 v8, v50, v51 offset0:2 offset1:3
	s_waitcnt vmcnt(8)
	v_add_u32_e32 v8, 0x7070, v3
	ds_write2_b32 v8, v52, v53 offset1:1
	ds_write2_b32 v8, v54, v55 offset0:2 offset1:3
	s_waitcnt vmcnt(7)
	v_add_u32_e32 v8, 0x8080, v3
	ds_write2_b32 v8, v56, v57 offset1:1
	ds_write2_b32 v8, v58, v59 offset0:2 offset1:3
	s_waitcnt vmcnt(6)
	v_add_u32_e32 v8, 0x9090, v3
	ds_write2_b32 v8, v60, v61 offset1:1
	ds_write2_b32 v8, v62, v63 offset0:2 offset1:3
	s_waitcnt vmcnt(5)
	v_add_u32_e32 v8, 0xa0a0, v3
	ds_write2_b32 v8, v64, v65 offset1:1
	ds_write2_b32 v8, v66, v67 offset0:2 offset1:3
	s_waitcnt vmcnt(4)
	v_add_u32_e32 v8, 0xb0b0, v3
	ds_write2_b32 v8, v68, v69 offset1:1
	ds_write2_b32 v8, v70, v71 offset0:2 offset1:3
	s_waitcnt vmcnt(3)
	v_add_u32_e32 v8, 0xc0c0, v3
	ds_write2_b32 v8, v72, v73 offset1:1
	ds_write2_b32 v8, v74, v75 offset0:2 offset1:3
	s_waitcnt vmcnt(2)
	v_add_u32_e32 v8, 0xd0d0, v3
	ds_write2_b32 v8, v76, v77 offset1:1
	ds_write2_b32 v8, v78, v79 offset0:2 offset1:3
	s_waitcnt vmcnt(1)
	v_add_u32_e32 v8, 0xe0e0, v3
	ds_write2_b32 v8, v80, v81 offset1:1
	ds_write2_b32 v8, v82, v83 offset0:2 offset1:3
	s_waitcnt vmcnt(0)
	v_add_u32_e32 v8, 0xf0f0, v3
	ds_write2_b32 v8, v84, v85 offset1:1
	ds_write2_b32 v8, v86, v87 offset0:2 offset1:3
	v_lshlrev_b32_e32 v0, 3, v2
	v_and_b32_e32 v3, 56, v0
	v_mov_b32_e32 v4, s17
	v_lshlrev_b32_e32 v160, 1, v3
	v_ashrrev_i32_e32 v8, 3, v2
	v_mad_u32_u24 v3, v3, s36, v4
	v_lshl_add_u32 v4, v8, 2, v3
	s_waitcnt lgkmcnt(0)
	s_barrier
	ds_read_b32 v5, v4
	ds_read_b32 v6, v4 offset:1028
	ds_read_b32 v7, v4 offset:2056
	ds_read_b32 v9, v4 offset:3084
	ds_read_b32 v10, v4 offset:4112
	ds_read_b32 v11, v4 offset:5140
	ds_read_b32 v12, v4 offset:6168
	ds_read_b32 v4, v4 offset:7196
	s_waitcnt lgkmcnt(4)
	v_bfe_u32 v20, v5, 16, 1
	v_add3_u32 v20, v5, v20, s94
	v_cvt_pk_bf16_f32 v9, v7, v9
	v_add_u32_e32 v8, s20, v8
	s_waitcnt lgkmcnt(0)
	v_bfe_u32 v19, v6, 16, 1
	v_mov_b32_e32 v5, v9
	v_ashrrev_i32_e32 v9, 31, v8
	v_lshl_add_u64 v[0:1], s[22:23], 0, v[160:161]
	v_add3_u32 v19, v6, v19, s94
	v_cvt_pk_bf16_f32 v10, v10, v11
	v_cvt_pk_bf16_f32 v4, v12, v4
	v_lshlrev_b64 v[8:9], 12, v[8:9]
	v_mov_b32_e32 v7, v4
	v_mov_b32_e32 v6, v10
	v_perm_b32 v4, v19, v20, s95
	v_lshl_add_u64 v[8:9], v[0:1], 0, v[8:9]
	global_store_dwordx4 v[8:9], v[4:7], off
	s_mov_b64 s[36:37], 0
	s_nop 0
	v_add_u32_e32 v4, 0x100, v2
	v_ashrrev_i32_e32 v8, 3, v4
	v_lshl_add_u32 v4, v8, 2, v3
	ds_read_b32 v5, v4
	ds_read_b32 v6, v4 offset:1028
	ds_read_b32 v7, v4 offset:2056
	ds_read_b32 v9, v4 offset:3084
	ds_read_b32 v10, v4 offset:4112
	ds_read_b32 v11, v4 offset:5140
	ds_read_b32 v12, v4 offset:6168
	ds_read_b32 v4, v4 offset:7196
	s_waitcnt lgkmcnt(4)
	v_bfe_u32 v20, v5, 16, 1
	v_add3_u32 v20, v5, v20, s94
	v_cvt_pk_bf16_f32 v9, v7, v9
	v_add_u32_e32 v8, s20, v8
	s_waitcnt lgkmcnt(0)
	v_bfe_u32 v19, v6, 16, 1
	v_mov_b32_e32 v5, v9
	v_ashrrev_i32_e32 v9, 31, v8
	v_add3_u32 v19, v6, v19, s94
	v_cvt_pk_bf16_f32 v10, v10, v11
	v_cvt_pk_bf16_f32 v4, v12, v4
	v_lshlrev_b64 v[8:9], 12, v[8:9]
	v_mov_b32_e32 v7, v4
	v_mov_b32_e32 v6, v10
	v_perm_b32 v4, v19, v20, s95
	v_lshl_add_u64 v[8:9], v[0:1], 0, v[8:9]
	global_store_dwordx4 v[8:9], v[4:7], off
	s_nop 1
	v_add_u32_e32 v4, 0x200, v2
	v_ashrrev_i32_e32 v8, 3, v4
	v_lshl_add_u32 v4, v8, 2, v3
	ds_read_b32 v5, v4
	ds_read_b32 v6, v4 offset:1028
	ds_read_b32 v7, v4 offset:2056
	ds_read_b32 v9, v4 offset:3084
	ds_read_b32 v10, v4 offset:4112
	ds_read_b32 v11, v4 offset:5140
	ds_read_b32 v12, v4 offset:6168
	ds_read_b32 v4, v4 offset:7196
	s_waitcnt lgkmcnt(4)
	v_bfe_u32 v20, v5, 16, 1
	v_add3_u32 v20, v5, v20, s94
	v_cvt_pk_bf16_f32 v9, v7, v9
	v_add_u32_e32 v8, s20, v8
	s_waitcnt lgkmcnt(0)
	v_bfe_u32 v19, v6, 16, 1
	v_mov_b32_e32 v5, v9
	v_ashrrev_i32_e32 v9, 31, v8
	v_add3_u32 v19, v6, v19, s94
	v_cvt_pk_bf16_f32 v10, v10, v11
	v_cvt_pk_bf16_f32 v4, v12, v4
	v_lshlrev_b64 v[8:9], 12, v[8:9]
	v_mov_b32_e32 v7, v4
	v_mov_b32_e32 v6, v10
	v_perm_b32 v4, v19, v20, s95
	v_lshl_add_u64 v[8:9], v[0:1], 0, v[8:9]
	global_store_dwordx4 v[8:9], v[4:7], off
	s_nop 1
	v_add_u32_e32 v4, 0x300, v2
	v_ashrrev_i32_e32 v8, 3, v4
	v_lshl_add_u32 v4, v8, 2, v3
	ds_read_b32 v5, v4
	ds_read_b32 v6, v4 offset:1028
	ds_read_b32 v7, v4 offset:2056
	ds_read_b32 v9, v4 offset:3084
	ds_read_b32 v10, v4 offset:4112
	ds_read_b32 v11, v4 offset:5140
	ds_read_b32 v12, v4 offset:6168
	ds_read_b32 v4, v4 offset:7196
	s_waitcnt lgkmcnt(4)
	v_bfe_u32 v20, v5, 16, 1
	v_add3_u32 v20, v5, v20, s94
	v_cvt_pk_bf16_f32 v9, v7, v9
	v_add_u32_e32 v8, s20, v8
	s_waitcnt lgkmcnt(0)
	v_bfe_u32 v19, v6, 16, 1
	v_mov_b32_e32 v5, v9
	v_ashrrev_i32_e32 v9, 31, v8
	v_add3_u32 v19, v6, v19, s94
	v_cvt_pk_bf16_f32 v10, v10, v11
	v_cvt_pk_bf16_f32 v4, v12, v4
	v_lshlrev_b64 v[8:9], 12, v[8:9]
	v_mov_b32_e32 v7, v4
	v_mov_b32_e32 v6, v10
	v_perm_b32 v4, v19, v20, s95
	v_lshl_add_u64 v[8:9], v[0:1], 0, v[8:9]
	global_store_dwordx4 v[8:9], v[4:7], off
	s_nop 1
	v_add_u32_e32 v4, 0x400, v2
	v_ashrrev_i32_e32 v8, 3, v4
	v_lshl_add_u32 v4, v8, 2, v3
	ds_read_b32 v5, v4
	ds_read_b32 v6, v4 offset:1028
	ds_read_b32 v7, v4 offset:2056
	ds_read_b32 v9, v4 offset:3084
	ds_read_b32 v10, v4 offset:4112
	ds_read_b32 v11, v4 offset:5140
	ds_read_b32 v12, v4 offset:6168
	ds_read_b32 v4, v4 offset:7196
	s_waitcnt lgkmcnt(4)
	v_bfe_u32 v20, v5, 16, 1
	v_add3_u32 v20, v5, v20, s94
	v_cvt_pk_bf16_f32 v9, v7, v9
	v_add_u32_e32 v8, s20, v8
	s_waitcnt lgkmcnt(0)
	v_bfe_u32 v19, v6, 16, 1
	v_mov_b32_e32 v5, v9
	v_ashrrev_i32_e32 v9, 31, v8
	v_add3_u32 v19, v6, v19, s94
	v_cvt_pk_bf16_f32 v10, v10, v11
	v_cvt_pk_bf16_f32 v4, v12, v4
	v_lshlrev_b64 v[8:9], 12, v[8:9]
	v_mov_b32_e32 v7, v4
	v_mov_b32_e32 v6, v10
	v_perm_b32 v4, v19, v20, s95
	v_lshl_add_u64 v[8:9], v[0:1], 0, v[8:9]
	global_store_dwordx4 v[8:9], v[4:7], off
	s_nop 1
	v_add_u32_e32 v4, 0x500, v2
	v_ashrrev_i32_e32 v8, 3, v4
	v_lshl_add_u32 v4, v8, 2, v3
	ds_read_b32 v5, v4
	ds_read_b32 v6, v4 offset:1028
	ds_read_b32 v7, v4 offset:2056
	ds_read_b32 v9, v4 offset:3084
	ds_read_b32 v10, v4 offset:4112
	ds_read_b32 v11, v4 offset:5140
	ds_read_b32 v12, v4 offset:6168
	ds_read_b32 v4, v4 offset:7196
	s_waitcnt lgkmcnt(4)
	v_bfe_u32 v20, v5, 16, 1
	v_add3_u32 v20, v5, v20, s94
	v_cvt_pk_bf16_f32 v9, v7, v9
	v_add_u32_e32 v8, s20, v8
	s_waitcnt lgkmcnt(0)
	v_bfe_u32 v19, v6, 16, 1
	v_mov_b32_e32 v5, v9
	v_ashrrev_i32_e32 v9, 31, v8
	v_add3_u32 v19, v6, v19, s94
	v_cvt_pk_bf16_f32 v10, v10, v11
	v_cvt_pk_bf16_f32 v4, v12, v4
	v_lshlrev_b64 v[8:9], 12, v[8:9]
	v_mov_b32_e32 v7, v4
	v_mov_b32_e32 v6, v10
	v_perm_b32 v4, v19, v20, s95
	v_lshl_add_u64 v[8:9], v[0:1], 0, v[8:9]
	global_store_dwordx4 v[8:9], v[4:7], off
	s_nop 1
	v_add_u32_e32 v4, 0x600, v2
	v_ashrrev_i32_e32 v8, 3, v4
	v_lshl_add_u32 v4, v8, 2, v3
	ds_read_b32 v5, v4
	ds_read_b32 v6, v4 offset:1028
	ds_read_b32 v7, v4 offset:2056
	ds_read_b32 v9, v4 offset:3084
	ds_read_b32 v10, v4 offset:4112
	ds_read_b32 v11, v4 offset:5140
	ds_read_b32 v12, v4 offset:6168
	ds_read_b32 v4, v4 offset:7196
	s_waitcnt lgkmcnt(4)
	v_bfe_u32 v20, v5, 16, 1
	v_add3_u32 v20, v5, v20, s94
	v_cvt_pk_bf16_f32 v9, v7, v9
	v_add_u32_e32 v8, s20, v8
	s_waitcnt lgkmcnt(0)
	v_bfe_u32 v19, v6, 16, 1
	v_mov_b32_e32 v5, v9
	v_ashrrev_i32_e32 v9, 31, v8
	v_add3_u32 v19, v6, v19, s94
	v_cvt_pk_bf16_f32 v10, v10, v11
	v_cvt_pk_bf16_f32 v4, v12, v4
	v_lshlrev_b64 v[8:9], 12, v[8:9]
	v_mov_b32_e32 v7, v4
	v_mov_b32_e32 v6, v10
	v_perm_b32 v4, v19, v20, s95
	v_lshl_add_u64 v[8:9], v[0:1], 0, v[8:9]
	v_add_u32_e32 v2, 0x700, v2
	global_store_dwordx4 v[8:9], v[4:7], off
	s_nop 1
	v_ashrrev_i32_e32 v6, 3, v2
	v_lshl_add_u32 v2, v6, 2, v3
	ds_read_b32 v3, v2
	ds_read_b32 v4, v2 offset:1028
	ds_read_b32 v5, v2 offset:2056
	ds_read_b32 v7, v2 offset:3084
	ds_read_b32 v8, v2 offset:4112
	ds_read_b32 v9, v2 offset:5140
	ds_read_b32 v10, v2 offset:6168
	ds_read_b32 v2, v2 offset:7196
	s_waitcnt lgkmcnt(4)
	v_bfe_u32 v18, v3, 16, 1
	v_add3_u32 v18, v3, v18, s94
	v_cvt_pk_bf16_f32 v7, v5, v7
	v_add_u32_e32 v6, s20, v6
	s_waitcnt lgkmcnt(0)
	v_bfe_u32 v17, v4, 16, 1
	v_mov_b32_e32 v3, v7
	v_ashrrev_i32_e32 v7, 31, v6
	v_add3_u32 v17, v4, v17, s94
	v_cvt_pk_bf16_f32 v8, v8, v9
	v_cvt_pk_bf16_f32 v2, v10, v2
	v_lshlrev_b64 v[6:7], 12, v[6:7]
	v_mov_b32_e32 v5, v2
	v_mov_b32_e32 v4, v8
	v_perm_b32 v2, v17, v18, s95
	v_lshl_add_u64 v[0:1], v[0:1], 0, v[6:7]
	global_store_dwordx4 v[0:1], v[2:5], off
	s_barrier
